# v13: v12 + grid barrier: each workgroup starts the XCD L2 write-back at arrival
# baseline (speedup 1.0000x reference)
; __device__ __forceinline__ unsigned xb_ld(unsigned* p)              { return __hip_atomic_load(p, __ATOMIC_RELAXED, __HIP_MEMORY_SCOPE_AGENT); }
; __device__ __forceinline__ void xcd_barrier_complete(unsigned* bar, unsigned x, unsigned& nloc, unsigned& nx) {
;     const unsigned G = gridDim.x * gridDim.y * gridDim.z;
;     unsigned sum, cnt, mine, sp = 0u;
;     for (;;) {
;         sum = 0u; cnt = 0u; mine = 0u;
; #pragma unroll
;         for (unsigned j = 0; j < 16; ++j) { const unsigned c = xb_ld(&bar[XB_XCNT(j)]); sum += c; cnt += (c > 0u) ? 1u : 0u; mine = (j == x) ? c : mine; }
; __device__ __forceinline__ void xcd_barrier(const XcdBarrier& b) {
;     asm volatile("s_waitcnt vmcnt(0)" ::: "memory");
;     __syncthreads();
;     if (threadIdx.x == 0) {
;         unsigned* bar = b.bar;
;         __builtin_amdgcn_s_waitcnt(0);
;         unsigned nloc = b.st[0], nx = b.st[1];
;         if (nloc == 0u) { xcd_barrier_complete(bar, b.x, nloc, nx); b.st[0] = nloc; b.st[1] = nx; }
.LBB0_55:
	s_cmp_gt_i32 s55, 1
	v_readlane_b32 s6, v255, 20
	s_cselect_b64 s[0:1], -1, 0
	v_readlane_b32 s7, v255, 21
	s_and_b64 s[6:7], s[6:7], s[0:1]
	s_andn2_b64 vcc, exec, s[6:7]
	s_cbranch_vccnz .LBB0_105
	s_waitcnt vmcnt(0)
	v_cmp_eq_u32_e32 vcc, 0, v0
	s_barrier
	s_and_saveexec_b64 s[6:7], vcc
	s_cbranch_execz .LBB0_104
	v_mov_b32_e32 v1, s95
	s_waitcnt vmcnt(0) expcnt(0) lgkmcnt(0)
	buffer_wbl2 sc1
	ds_read_b32 v3, v1
	ds_read_b32 v1, v1 offset:4
	s_waitcnt lgkmcnt(1)
	v_cmp_ne_u32_e32 vcc, 0, v3
	s_cbranch_vccnz .LBB0_72
	v_readlane_b32 s10, v255, 9
	v_readlane_b32 s11, v255, 10
	s_load_dwordx2 s[14:15], s[10:11], 0x4
	s_add_u32 s10, s52, 0x4200
	s_addc_u32 s11, s53, 0
	s_add_u32 s12, s52, 0x4400
	s_addc_u32 s13, s53, 0
	s_waitcnt lgkmcnt(0)
	s_mul_i32 s3, s14, s60
	s_add_u32 s14, s52, 0x4500
	s_mul_i32 s3, s3, s15
	s_addc_u32 s15, s53, 0
	s_add_u32 s18, s52, 0x4600
	s_addc_u32 s19, s53, 0
	s_add_u32 s20, s52, 0x4700
	s_addc_u32 s21, s53, 0
	s_add_u32 s24, s52, 0x4800
	s_addc_u32 s25, s53, 0
	s_add_u32 s42, s52, 0x4900
	s_addc_u32 s43, s53, 0
	s_add_u32 s44, s52, 0x4a00
	s_addc_u32 s45, s53, 0
	s_add_u32 s46, s52, 0x4b00
	s_addc_u32 s47, s53, 0
	s_add_u32 s48, s52, 0x4c00
	s_addc_u32 s49, s53, 0
	s_add_u32 s50, s52, 0x4d00
	s_addc_u32 s51, s53, 0
	s_add_u32 s72, s52, 0x4e00
	s_addc_u32 s73, s53, 0
	s_add_u32 s74, s52, 0x4f00
	s_addc_u32 s75, s53, 0
	s_add_u32 s76, s52, 0x5000
	s_addc_u32 s77, s53, 0
	s_add_u32 s78, s52, 0x5100
	s_addc_u32 s79, s53, 0
	s_add_u32 s80, s52, 0x5200
	s_addc_u32 s81, s53, 0
	s_add_u32 s82, s52, 0x5300
	s_addc_u32 s83, s53, 0
	s_mov_b32 s26, 1
	v_mov_b32_e32 v17, 0
	s_branch .LBB0_60

; __device__ __forceinline__ unsigned xb_ld(unsigned* p)              { return __hip_atomic_load(p, __ATOMIC_RELAXED, __HIP_MEMORY_SCOPE_AGENT); }
; __device__ __forceinline__ void xcd_barrier_complete(unsigned* bar, unsigned x, unsigned& nloc, unsigned& nx) {
;     const unsigned G = gridDim.x * gridDim.y * gridDim.z;
;     unsigned sum, cnt, mine, sp = 0u;
;     for (;;) {
;         sum = 0u; cnt = 0u; mine = 0u;
; #pragma unroll
;         for (unsigned j = 0; j < 16; ++j) { const unsigned c = xb_ld(&bar[XB_XCNT(j)]); sum += c; cnt += (c > 0u) ? 1u : 0u; mine = (j == x) ? c : mine; }
; __device__ __forceinline__ void xcd_barrier(const XcdBarrier& b) {
;     asm volatile("s_waitcnt vmcnt(0)" ::: "memory");
;     __syncthreads();
;     if (threadIdx.x == 0) {
;         unsigned* bar = b.bar;
;         __builtin_amdgcn_s_waitcnt(0);
;         unsigned nloc = b.st[0], nx = b.st[1];
;         if (nloc == 0u) { xcd_barrier_complete(bar, b.x, nloc, nx); b.st[0] = nloc; b.st[1] = nx; }
.LBB0_130:
	s_cmp_gt_i32 s55, 2
	s_cselect_b64 s[0:1], -1, 0
	s_and_b64 s[4:5], s[6:7], s[0:1]
	s_andn2_b64 vcc, exec, s[4:5]
	s_cbranch_vccnz .LBB0_180
	s_waitcnt vmcnt(0)
	v_cmp_eq_u32_e32 vcc, 0, v0
	s_barrier
	s_and_saveexec_b64 s[4:5], vcc
	s_cbranch_execz .LBB0_179
	v_mov_b32_e32 v1, s95
	s_waitcnt vmcnt(0) expcnt(0) lgkmcnt(0)
	buffer_wbl2 sc1
	ds_read_b32 v3, v1
	ds_read_b32 v1, v1 offset:4
	s_waitcnt lgkmcnt(1)
	v_cmp_ne_u32_e32 vcc, 0, v3
	s_cbranch_vccnz .LBB0_147
	v_readlane_b32 s6, v255, 9
	v_readlane_b32 s7, v255, 10
	s_load_dwordx2 s[14:15], s[6:7], 0x4
	s_add_u32 s6, s52, 0x4200
	s_addc_u32 s7, s53, 0
	s_add_u32 s10, s52, 0x4400
	s_addc_u32 s11, s53, 0
	s_waitcnt lgkmcnt(0)
	s_mul_i32 s3, s14, s60
	s_add_u32 s14, s52, 0x4500
	s_mul_i32 s3, s3, s15
	s_addc_u32 s15, s53, 0
	s_add_u32 s16, s52, 0x4600
	s_addc_u32 s17, s53, 0
	s_add_u32 s18, s52, 0x4700
	s_addc_u32 s19, s53, 0
	s_add_u32 s24, s52, 0x4800
	s_addc_u32 s25, s53, 0
	s_add_u32 s42, s52, 0x4900
	s_addc_u32 s43, s53, 0
	s_add_u32 s44, s52, 0x4a00
	s_addc_u32 s45, s53, 0
	s_add_u32 s46, s52, 0x4b00
	s_addc_u32 s47, s53, 0
	s_add_u32 s48, s52, 0x4c00
	s_addc_u32 s49, s53, 0
	s_add_u32 s50, s52, 0x4d00
	s_addc_u32 s51, s53, 0
	s_add_u32 s72, s52, 0x4e00
	s_addc_u32 s73, s53, 0
	s_add_u32 s74, s52, 0x4f00
	s_addc_u32 s75, s53, 0
	s_add_u32 s76, s52, 0x5000
	s_addc_u32 s77, s53, 0
	s_add_u32 s78, s52, 0x5100
	s_addc_u32 s79, s53, 0
	s_add_u32 s80, s52, 0x5200
	s_addc_u32 s81, s53, 0
	s_add_u32 s82, s52, 0x5300
	s_addc_u32 s83, s53, 0
	s_mov_b32 s26, 1
	v_mov_b32_e32 v17, 0
	s_branch .LBB0_135

; __device__ __forceinline__ unsigned xb_ld(unsigned* p)              { return __hip_atomic_load(p, __ATOMIC_RELAXED, __HIP_MEMORY_SCOPE_AGENT); }
; __device__ __forceinline__ void xcd_barrier_complete(unsigned* bar, unsigned x, unsigned& nloc, unsigned& nx) {
;     const unsigned G = gridDim.x * gridDim.y * gridDim.z;
;     unsigned sum, cnt, mine, sp = 0u;
;     for (;;) {
;         sum = 0u; cnt = 0u; mine = 0u;
; #pragma unroll
;         for (unsigned j = 0; j < 16; ++j) { const unsigned c = xb_ld(&bar[XB_XCNT(j)]); sum += c; cnt += (c > 0u) ? 1u : 0u; mine = (j == x) ? c : mine; }
; __device__ __forceinline__ void xcd_barrier(const XcdBarrier& b) {
;     asm volatile("s_waitcnt vmcnt(0)" ::: "memory");
;     __syncthreads();
;     if (threadIdx.x == 0) {
;         unsigned* bar = b.bar;
;         __builtin_amdgcn_s_waitcnt(0);
;         unsigned nloc = b.st[0], nx = b.st[1];
;         if (nloc == 0u) { xcd_barrier_complete(bar, b.x, nloc, nx); b.st[0] = nloc; b.st[1] = nx; }
.LBB0_223:
	s_cmp_gt_u32 s55, 3
	s_cselect_b64 s[0:1], -1, 0
	s_and_b64 s[0:1], s[14:15], s[0:1]
	s_andn2_b64 vcc, exec, s[0:1]
	s_cbranch_vccnz .LBB0_273
	s_waitcnt vmcnt(0)
	v_cmp_eq_u32_e32 vcc, 0, v0
	s_waitcnt lgkmcnt(0)
	s_barrier
	s_and_saveexec_b64 s[0:1], vcc
	s_cbranch_execz .LBB0_272
	v_mov_b32_e32 v1, s95
	s_waitcnt vmcnt(0) expcnt(0) lgkmcnt(0)
	buffer_wbl2 sc1
	ds_read_b32 v3, v1
	ds_read_b32 v1, v1 offset:4
	s_waitcnt lgkmcnt(1)
	v_cmp_ne_u32_e32 vcc, 0, v3
	s_cbranch_vccnz .LBB0_240
	v_readlane_b32 s4, v255, 9
	v_readlane_b32 s5, v255, 10
	s_load_dwordx2 s[8:9], s[4:5], 0x4
	s_add_u32 s4, s52, 0x4200
	s_addc_u32 s5, s53, 0
	s_add_u32 s6, s52, 0x4400
	s_addc_u32 s7, s53, 0
	s_waitcnt lgkmcnt(0)
	s_mul_i32 s3, s8, s60
	s_add_u32 s8, s52, 0x4500
	s_mul_i32 s3, s3, s9
	s_addc_u32 s9, s53, 0
	s_add_u32 s12, s52, 0x4600
	s_addc_u32 s13, s53, 0
	s_add_u32 s14, s52, 0x4700
	s_addc_u32 s15, s53, 0
	s_add_u32 s16, s52, 0x4800
	s_addc_u32 s17, s53, 0
	s_add_u32 s18, s52, 0x4900
	s_addc_u32 s19, s53, 0
	s_add_u32 s24, s52, 0x4a00
	s_addc_u32 s25, s53, 0
	s_add_u32 s44, s52, 0x4b00
	s_addc_u32 s45, s53, 0
	s_add_u32 s46, s52, 0x4c00
	s_addc_u32 s47, s53, 0
	s_add_u32 s48, s52, 0x4d00
	s_addc_u32 s49, s53, 0
	s_add_u32 s50, s52, 0x4e00
	s_addc_u32 s51, s53, 0
	s_add_u32 s72, s52, 0x4f00
	s_addc_u32 s73, s53, 0
	s_add_u32 s74, s52, 0x5000
	s_addc_u32 s75, s53, 0
	s_add_u32 s76, s52, 0x5100
	s_addc_u32 s77, s53, 0
	s_add_u32 s78, s52, 0x5200
	s_addc_u32 s79, s53, 0
	s_add_u32 s80, s52, 0x5300
	s_addc_u32 s81, s53, 0
	s_mov_b32 s26, 1
	v_mov_b32_e32 v17, 0
	s_branch .LBB0_228

; __device__ __forceinline__ unsigned xb_ld(unsigned* p)              { return __hip_atomic_load(p, __ATOMIC_RELAXED, __HIP_MEMORY_SCOPE_AGENT); }
; __device__ __forceinline__ void xcd_barrier_complete(unsigned* bar, unsigned x, unsigned& nloc, unsigned& nx) {
;     const unsigned G = gridDim.x * gridDim.y * gridDim.z;
;     unsigned sum, cnt, mine, sp = 0u;
;     for (;;) {
;         sum = 0u; cnt = 0u; mine = 0u;
; #pragma unroll
;         for (unsigned j = 0; j < 16; ++j) { const unsigned c = xb_ld(&bar[XB_XCNT(j)]); sum += c; cnt += (c > 0u) ? 1u : 0u; mine = (j == x) ? c : mine; }
; __device__ __forceinline__ void xcd_barrier(const XcdBarrier& b) {
;     asm volatile("s_waitcnt vmcnt(0)" ::: "memory");
;     __syncthreads();
;     if (threadIdx.x == 0) {
;         unsigned* bar = b.bar;
;         __builtin_amdgcn_s_waitcnt(0);
;         unsigned nloc = b.st[0], nx = b.st[1];
;         if (nloc == 0u) { xcd_barrier_complete(bar, b.x, nloc, nx); b.st[0] = nloc; b.st[1] = nx; }
.LBB0_393:
	s_cmp_gt_i32 s55, 5
	s_cselect_b64 s[0:1], -1, 0
	s_and_b64 s[4:5], s[6:7], s[0:1]
	s_andn2_b64 vcc, exec, s[4:5]
	s_cbranch_vccnz .LBB0_443
	s_waitcnt vmcnt(0)
	v_cmp_eq_u32_e32 vcc, 0, v0
	s_waitcnt lgkmcnt(0)
	s_barrier
	s_and_saveexec_b64 s[4:5], vcc
	s_cbranch_execz .LBB0_442
	v_mov_b32_e32 v1, s95
	s_waitcnt vmcnt(0) expcnt(0) lgkmcnt(0)
	buffer_wbl2 sc1
	ds_read_b32 v3, v1
	ds_read_b32 v1, v1 offset:4
	s_waitcnt lgkmcnt(1)
	v_cmp_ne_u32_e32 vcc, 0, v3
	s_cbranch_vccnz .LBB0_410
	v_readlane_b32 s6, v255, 9
	v_readlane_b32 s7, v255, 10
	s_load_dwordx2 s[10:11], s[6:7], 0x4
	s_add_u32 s6, s52, 0x4200
	s_addc_u32 s7, s53, 0
	s_add_u32 s8, s52, 0x4400
	s_addc_u32 s9, s53, 0
	s_waitcnt lgkmcnt(0)
	s_mul_i32 s3, s10, s60
	s_add_u32 s10, s52, 0x4500
	s_mul_i32 s3, s3, s11
	s_addc_u32 s11, s53, 0
	s_add_u32 s12, s52, 0x4600
	s_addc_u32 s13, s53, 0
	s_add_u32 s14, s52, 0x4700
	s_addc_u32 s15, s53, 0
	s_add_u32 s16, s52, 0x4800
	s_addc_u32 s17, s53, 0
	s_add_u32 s18, s52, 0x4900
	s_addc_u32 s19, s53, 0
	s_add_u32 s46, s52, 0x4a00
	s_addc_u32 s47, s53, 0
	s_add_u32 s48, s52, 0x4b00
	s_addc_u32 s49, s53, 0
	s_add_u32 s50, s52, 0x4c00
	s_addc_u32 s51, s53, 0
	s_add_u32 s70, s52, 0x4d00
	s_addc_u32 s71, s53, 0
	s_add_u32 s72, s52, 0x4e00
	s_addc_u32 s73, s53, 0
	s_add_u32 s74, s52, 0x4f00
	s_addc_u32 s75, s53, 0
	s_add_u32 s76, s52, 0x5000
	s_addc_u32 s77, s53, 0
	s_add_u32 s78, s52, 0x5100
	s_addc_u32 s79, s53, 0
	s_add_u32 s80, s52, 0x5200
	s_addc_u32 s81, s53, 0
	s_add_u32 s82, s52, 0x5300
	s_addc_u32 s83, s53, 0
	s_mov_b32 s26, 1
	v_mov_b32_e32 v17, 0
	s_branch .LBB0_398

; __device__ __forceinline__ unsigned xb_ld(unsigned* p)              { return __hip_atomic_load(p, __ATOMIC_RELAXED, __HIP_MEMORY_SCOPE_AGENT); }
; __device__ __forceinline__ void xcd_barrier_complete(unsigned* bar, unsigned x, unsigned& nloc, unsigned& nx) {
;     const unsigned G = gridDim.x * gridDim.y * gridDim.z;
;     unsigned sum, cnt, mine, sp = 0u;
;     for (;;) {
;         sum = 0u; cnt = 0u; mine = 0u;
; #pragma unroll
;         for (unsigned j = 0; j < 16; ++j) { const unsigned c = xb_ld(&bar[XB_XCNT(j)]); sum += c; cnt += (c > 0u) ? 1u : 0u; mine = (j == x) ? c : mine; }
; __device__ __forceinline__ void xcd_barrier(const XcdBarrier& b) {
;     asm volatile("s_waitcnt vmcnt(0)" ::: "memory");
;     __syncthreads();
;     if (threadIdx.x == 0) {
;         unsigned* bar = b.bar;
;         __builtin_amdgcn_s_waitcnt(0);
;         unsigned nloc = b.st[0], nx = b.st[1];
;         if (nloc == 0u) { xcd_barrier_complete(bar, b.x, nloc, nx); b.st[0] = nloc; b.st[1] = nx; }
.LBB0_467:
	s_cmp_gt_i32 s55, 6
	s_cselect_b64 s[0:1], -1, 0
	s_and_b64 s[4:5], s[70:71], s[0:1]
	s_andn2_b64 vcc, exec, s[4:5]
	s_cbranch_vccnz .LBB0_517
	s_waitcnt vmcnt(0)
	v_cmp_eq_u32_e32 vcc, 0, v0
	s_waitcnt lgkmcnt(0)
	s_barrier
	s_and_saveexec_b64 s[4:5], vcc
	s_cbranch_execz .LBB0_516
	v_mov_b32_e32 v1, s95
	s_waitcnt vmcnt(0) expcnt(0) lgkmcnt(0)
	buffer_wbl2 sc1
	ds_read_b32 v3, v1
	ds_read_b32 v1, v1 offset:4
	s_waitcnt lgkmcnt(1)
	v_cmp_ne_u32_e32 vcc, 0, v3
	s_cbranch_vccnz .LBB0_484
	v_readlane_b32 s6, v255, 9
	v_readlane_b32 s7, v255, 10
	s_load_dwordx2 s[10:11], s[6:7], 0x4
	s_add_u32 s6, s52, 0x4200
	s_addc_u32 s7, s53, 0
	s_add_u32 s8, s52, 0x4400
	s_addc_u32 s9, s53, 0
	s_waitcnt lgkmcnt(0)
	s_mul_i32 s3, s10, s60
	s_add_u32 s10, s52, 0x4500
	s_mul_i32 s3, s3, s11
	s_addc_u32 s11, s53, 0
	s_add_u32 s12, s52, 0x4600
	s_addc_u32 s13, s53, 0
	s_add_u32 s14, s52, 0x4700
	s_addc_u32 s15, s53, 0
	s_add_u32 s16, s52, 0x4800
	s_addc_u32 s17, s53, 0
	s_add_u32 s18, s52, 0x4900
	s_addc_u32 s19, s53, 0
	s_add_u32 s22, s52, 0x4a00
	s_addc_u32 s23, s53, 0
	s_add_u32 s70, s52, 0x4b00
	s_addc_u32 s71, s53, 0
	s_add_u32 s72, s52, 0x4c00
	s_addc_u32 s73, s53, 0
	s_add_u32 s74, s52, 0x4d00
	s_addc_u32 s75, s53, 0
	s_add_u32 s76, s52, 0x4e00
	s_addc_u32 s77, s53, 0
	s_add_u32 s78, s52, 0x4f00
	s_addc_u32 s79, s53, 0
	s_add_u32 s80, s52, 0x5000
	s_addc_u32 s81, s53, 0
	s_add_u32 s82, s52, 0x5100
	s_addc_u32 s83, s53, 0
	s_add_u32 s84, s52, 0x5200
	s_addc_u32 s85, s53, 0
	s_add_u32 s86, s52, 0x5300
	s_addc_u32 s87, s53, 0
	s_mov_b32 s26, 1
	v_mov_b32_e32 v17, 0
	s_branch .LBB0_472

; __device__ __forceinline__ unsigned xb_ld(unsigned* p)              { return __hip_atomic_load(p, __ATOMIC_RELAXED, __HIP_MEMORY_SCOPE_AGENT); }
; __device__ __forceinline__ void xcd_barrier_complete(unsigned* bar, unsigned x, unsigned& nloc, unsigned& nx) {
;     const unsigned G = gridDim.x * gridDim.y * gridDim.z;
;     unsigned sum, cnt, mine, sp = 0u;
;     for (;;) {
;         sum = 0u; cnt = 0u; mine = 0u;
; #pragma unroll
;         for (unsigned j = 0; j < 16; ++j) { const unsigned c = xb_ld(&bar[XB_XCNT(j)]); sum += c; cnt += (c > 0u) ? 1u : 0u; mine = (j == x) ? c : mine; }
; __device__ __forceinline__ void xcd_barrier(const XcdBarrier& b) {
;     asm volatile("s_waitcnt vmcnt(0)" ::: "memory");
;     __syncthreads();
;     if (threadIdx.x == 0) {
;         unsigned* bar = b.bar;
;         __builtin_amdgcn_s_waitcnt(0);
;         unsigned nloc = b.st[0], nx = b.st[1];
;         if (nloc == 0u) { xcd_barrier_complete(bar, b.x, nloc, nx); b.st[0] = nloc; b.st[1] = nx; }
.LBB0_544:
	s_cmp_gt_i32 s55, 7
	s_cselect_b64 s[0:1], -1, 0
	s_and_b64 s[4:5], s[22:23], s[0:1]
	s_andn2_b64 vcc, exec, s[4:5]
	s_cbranch_vccnz .LBB0_594
	s_waitcnt vmcnt(0)
	v_cmp_eq_u32_e32 vcc, 0, v0
	s_waitcnt lgkmcnt(0)
	s_barrier
	s_and_saveexec_b64 s[4:5], vcc
	s_cbranch_execz .LBB0_593
	v_mov_b32_e32 v1, s95
	s_waitcnt vmcnt(0) expcnt(0) lgkmcnt(0)
	buffer_wbl2 sc1
	ds_read_b32 v3, v1
	ds_read_b32 v1, v1 offset:4
	s_waitcnt lgkmcnt(1)
	v_cmp_ne_u32_e32 vcc, 0, v3
	s_cbranch_vccnz .LBB0_561
	v_readlane_b32 s6, v255, 9
	v_readlane_b32 s7, v255, 10
	s_load_dwordx2 s[10:11], s[6:7], 0x4
	s_add_u32 s6, s52, 0x4200
	s_addc_u32 s7, s53, 0
	s_add_u32 s8, s52, 0x4400
	s_addc_u32 s9, s53, 0
	s_waitcnt lgkmcnt(0)
	s_mul_i32 s3, s10, s60
	s_add_u32 s10, s52, 0x4500
	s_mul_i32 s3, s3, s11
	s_addc_u32 s11, s53, 0
	s_add_u32 s12, s52, 0x4600
	s_addc_u32 s13, s53, 0
	s_add_u32 s14, s52, 0x4700
	s_addc_u32 s15, s53, 0
	s_add_u32 s16, s52, 0x4800
	s_addc_u32 s17, s53, 0
	s_add_u32 s22, s52, 0x4900
	s_addc_u32 s23, s53, 0
	s_add_u32 s50, s52, 0x4a00
	s_addc_u32 s51, s53, 0
	s_add_u32 s70, s52, 0x4b00
	s_addc_u32 s71, s53, 0
	s_add_u32 s72, s52, 0x4c00
	s_addc_u32 s73, s53, 0
	s_add_u32 s74, s52, 0x4d00
	s_addc_u32 s75, s53, 0
	s_add_u32 s76, s52, 0x4e00
	s_addc_u32 s77, s53, 0
	s_add_u32 s78, s52, 0x4f00
	s_addc_u32 s79, s53, 0
	s_add_u32 s80, s52, 0x5000
	s_addc_u32 s81, s53, 0
	s_add_u32 s82, s52, 0x5100
	s_addc_u32 s83, s53, 0
	s_add_u32 s84, s52, 0x5200
	s_addc_u32 s85, s53, 0
	s_add_u32 s86, s52, 0x5300
	s_addc_u32 s87, s53, 0
	s_mov_b32 s26, 1
	v_mov_b32_e32 v17, 0
	s_branch .LBB0_549

; __device__ __forceinline__ unsigned xb_ld(unsigned* p)              { return __hip_atomic_load(p, __ATOMIC_RELAXED, __HIP_MEMORY_SCOPE_AGENT); }
; __device__ __forceinline__ void xcd_barrier_complete(unsigned* bar, unsigned x, unsigned& nloc, unsigned& nx) {
;     const unsigned G = gridDim.x * gridDim.y * gridDim.z;
;     unsigned sum, cnt, mine, sp = 0u;
;     for (;;) {
;         sum = 0u; cnt = 0u; mine = 0u;
; #pragma unroll
;         for (unsigned j = 0; j < 16; ++j) { const unsigned c = xb_ld(&bar[XB_XCNT(j)]); sum += c; cnt += (c > 0u) ? 1u : 0u; mine = (j == x) ? c : mine; }
; __device__ __forceinline__ void xcd_barrier(const XcdBarrier& b) {
;     asm volatile("s_waitcnt vmcnt(0)" ::: "memory");
;     __syncthreads();
;     if (threadIdx.x == 0) {
;         unsigned* bar = b.bar;
;         __builtin_amdgcn_s_waitcnt(0);
;         unsigned nloc = b.st[0], nx = b.st[1];
;         if (nloc == 0u) { xcd_barrier_complete(bar, b.x, nloc, nx); b.st[0] = nloc; b.st[1] = nx; }
.LBB0_614:
	s_cmp_gt_i32 s55, 8
	s_cselect_b64 s[0:1], -1, 0
	s_and_b64 s[4:5], s[16:17], s[0:1]
	s_andn2_b64 vcc, exec, s[4:5]
	s_cbranch_vccnz .LBB0_664
	s_waitcnt vmcnt(0)
	v_cmp_eq_u32_e32 vcc, 0, v0
	s_waitcnt lgkmcnt(0)
	s_barrier
	s_and_saveexec_b64 s[4:5], vcc
	s_cbranch_execz .LBB0_663
	v_mov_b32_e32 v1, s95
	s_waitcnt vmcnt(0) expcnt(0) lgkmcnt(0)
	buffer_wbl2 sc1
	ds_read_b32 v3, v1
	ds_read_b32 v1, v1 offset:4
	s_waitcnt lgkmcnt(1)
	v_cmp_ne_u32_e32 vcc, 0, v3
	s_cbranch_vccnz .LBB0_631
	v_readlane_b32 s6, v255, 9
	v_readlane_b32 s7, v255, 10
	s_load_dwordx2 s[10:11], s[6:7], 0x4
	s_add_u32 s6, s52, 0x4200
	s_addc_u32 s7, s53, 0
	s_add_u32 s8, s52, 0x4400
	s_addc_u32 s9, s53, 0
	s_waitcnt lgkmcnt(0)
	s_mul_i32 s3, s10, s60
	s_add_u32 s10, s52, 0x4500
	s_mul_i32 s3, s3, s11
	s_addc_u32 s11, s53, 0
	s_add_u32 s12, s52, 0x4600
	s_addc_u32 s13, s53, 0
	s_add_u32 s14, s52, 0x4700
	s_addc_u32 s15, s53, 0
	s_add_u32 s16, s52, 0x4800
	s_addc_u32 s17, s53, 0
	s_add_u32 s22, s52, 0x4900
	s_addc_u32 s23, s53, 0
	s_add_u32 s36, s52, 0x4a00
	s_addc_u32 s37, s53, 0
	s_add_u32 s38, s52, 0x4b00
	s_addc_u32 s39, s53, 0
	s_add_u32 s40, s52, 0x4c00
	s_addc_u32 s41, s53, 0
	s_add_u32 s44, s52, 0x4d00
	s_addc_u32 s45, s53, 0
	s_add_u32 s46, s52, 0x4e00
	s_addc_u32 s47, s53, 0
	s_add_u32 s48, s52, 0x4f00
	s_addc_u32 s49, s53, 0
	s_add_u32 s50, s52, 0x5000
	s_addc_u32 s51, s53, 0
	s_add_u32 s70, s52, 0x5100
	s_addc_u32 s71, s53, 0
	s_add_u32 s72, s52, 0x5200
	s_addc_u32 s73, s53, 0
	s_add_u32 s74, s52, 0x5300
	s_addc_u32 s75, s53, 0
	s_mov_b32 s26, 1
	v_mov_b32_e32 v17, 0
	s_branch .LBB0_619

; __device__ __forceinline__ unsigned xb_ld(unsigned* p)              { return __hip_atomic_load(p, __ATOMIC_RELAXED, __HIP_MEMORY_SCOPE_AGENT); }
; __device__ __forceinline__ void xcd_barrier_complete(unsigned* bar, unsigned x, unsigned& nloc, unsigned& nx) {
;     const unsigned G = gridDim.x * gridDim.y * gridDim.z;
;     unsigned sum, cnt, mine, sp = 0u;
;     for (;;) {
;         sum = 0u; cnt = 0u; mine = 0u;
; #pragma unroll
;         for (unsigned j = 0; j < 16; ++j) { const unsigned c = xb_ld(&bar[XB_XCNT(j)]); sum += c; cnt += (c > 0u) ? 1u : 0u; mine = (j == x) ? c : mine; }
; __device__ __forceinline__ void xcd_barrier(const XcdBarrier& b) {
;     asm volatile("s_waitcnt vmcnt(0)" ::: "memory");
;     __syncthreads();
;     if (threadIdx.x == 0) {
;         unsigned* bar = b.bar;
;         __builtin_amdgcn_s_waitcnt(0);
;         unsigned nloc = b.st[0], nx = b.st[1];
;         if (nloc == 0u) { xcd_barrier_complete(bar, b.x, nloc, nx); b.st[0] = nloc; b.st[1] = nx; }
.LBB0_691:
	s_cmp_gt_i32 s55, 9
	s_cselect_b64 s[0:1], -1, 0
	s_and_b64 s[4:5], s[4:5], s[0:1]
	s_andn2_b64 vcc, exec, s[4:5]
	s_cbranch_vccnz .LBB0_741
	s_waitcnt vmcnt(0)
	v_cmp_eq_u32_e32 vcc, 0, v0
	s_waitcnt lgkmcnt(0)
	s_barrier
	s_and_saveexec_b64 s[4:5], vcc
	s_cbranch_execz .LBB0_740
	v_mov_b32_e32 v1, s95
	s_waitcnt vmcnt(0) expcnt(0) lgkmcnt(0)
	buffer_wbl2 sc1
	ds_read_b32 v3, v1
	ds_read_b32 v1, v1 offset:4
	s_waitcnt lgkmcnt(1)
	v_cmp_ne_u32_e32 vcc, 0, v3
	s_cbranch_vccnz .LBB0_708
	v_readlane_b32 s6, v255, 9
	v_readlane_b32 s7, v255, 10
	s_load_dwordx2 s[10:11], s[6:7], 0x4
	s_add_u32 s6, s52, 0x4200
	s_addc_u32 s7, s53, 0
	s_add_u32 s8, s52, 0x4400
	s_addc_u32 s9, s53, 0
	s_waitcnt lgkmcnt(0)
	s_mul_i32 s3, s10, s60
	s_add_u32 s10, s52, 0x4500
	s_mul_i32 s3, s3, s11
	s_addc_u32 s11, s53, 0
	s_add_u32 s12, s52, 0x4600
	s_addc_u32 s13, s53, 0
	s_add_u32 s14, s52, 0x4700
	s_addc_u32 s15, s53, 0
	s_add_u32 s16, s52, 0x4800
	s_addc_u32 s17, s53, 0
	s_add_u32 s22, s52, 0x4900
	s_addc_u32 s23, s53, 0
	s_add_u32 s36, s52, 0x4a00
	s_addc_u32 s37, s53, 0
	s_add_u32 s38, s52, 0x4b00
	s_addc_u32 s39, s53, 0
	s_add_u32 s40, s52, 0x4c00
	s_addc_u32 s41, s53, 0
	s_add_u32 s44, s52, 0x4d00
	s_addc_u32 s45, s53, 0
	s_add_u32 s46, s52, 0x4e00
	s_addc_u32 s47, s53, 0
	s_add_u32 s48, s52, 0x4f00
	s_addc_u32 s49, s53, 0
	s_add_u32 s50, s52, 0x5000
	s_addc_u32 s51, s53, 0
	s_add_u32 s68, s52, 0x5100
	s_addc_u32 s69, s53, 0
	s_add_u32 s70, s52, 0x5200
	s_addc_u32 s71, s53, 0
	s_add_u32 s72, s52, 0x5300
	s_addc_u32 s73, s53, 0
	s_mov_b32 s26, 1
	v_mov_b32_e32 v17, 0
	s_branch .LBB0_696

; __device__ __forceinline__ unsigned xb_ld(unsigned* p)              { return __hip_atomic_load(p, __ATOMIC_RELAXED, __HIP_MEMORY_SCOPE_AGENT); }
; __device__ __forceinline__ void xcd_barrier_complete(unsigned* bar, unsigned x, unsigned& nloc, unsigned& nx) {
;     const unsigned G = gridDim.x * gridDim.y * gridDim.z;
;     unsigned sum, cnt, mine, sp = 0u;
;     for (;;) {
;         sum = 0u; cnt = 0u; mine = 0u;
; #pragma unroll
;         for (unsigned j = 0; j < 16; ++j) { const unsigned c = xb_ld(&bar[XB_XCNT(j)]); sum += c; cnt += (c > 0u) ? 1u : 0u; mine = (j == x) ? c : mine; }
; __device__ __forceinline__ void xcd_barrier(const XcdBarrier& b) {
;     asm volatile("s_waitcnt vmcnt(0)" ::: "memory");
;     __syncthreads();
;     if (threadIdx.x == 0) {
;         unsigned* bar = b.bar;
;         __builtin_amdgcn_s_waitcnt(0);
;         unsigned nloc = b.st[0], nx = b.st[1];
;         if (nloc == 0u) { xcd_barrier_complete(bar, b.x, nloc, nx); b.st[0] = nloc; b.st[1] = nx; }
.LBB0_780:
	s_cmp_gt_u32 s55, 10
	s_cselect_b64 s[0:1], -1, 0
	s_and_b64 s[0:1], s[6:7], s[0:1]
	s_andn2_b64 vcc, exec, s[0:1]
	s_cbranch_vccnz .LBB0_830
	s_waitcnt vmcnt(0)
	v_cmp_eq_u32_e32 vcc, 0, v0
	s_waitcnt lgkmcnt(0)
	s_barrier
	s_and_saveexec_b64 s[0:1], vcc
	s_cbranch_execz .LBB0_829
	v_mov_b32_e32 v1, s95
	s_waitcnt vmcnt(0) expcnt(0) lgkmcnt(0)
	buffer_wbl2 sc1
	ds_read_b32 v3, v1
	ds_read_b32 v1, v1 offset:4
	s_waitcnt lgkmcnt(1)
	v_cmp_ne_u32_e32 vcc, 0, v3
	s_cbranch_vccnz .LBB0_797
	v_readlane_b32 s4, v255, 9
	v_readlane_b32 s5, v255, 10
	s_load_dwordx2 s[8:9], s[4:5], 0x4
	s_add_u32 s4, s52, 0x4200
	s_addc_u32 s5, s53, 0
	s_add_u32 s6, s52, 0x4400
	s_addc_u32 s7, s53, 0
	s_waitcnt lgkmcnt(0)
	s_mul_i32 s3, s8, s60
	s_add_u32 s8, s52, 0x4500
	s_mul_i32 s3, s3, s9
	s_addc_u32 s9, s53, 0
	s_add_u32 s10, s52, 0x4600
	s_addc_u32 s11, s53, 0
	s_add_u32 s12, s52, 0x4700
	s_addc_u32 s13, s53, 0
	s_add_u32 s14, s52, 0x4800
	s_addc_u32 s15, s53, 0
	s_add_u32 s16, s52, 0x4900
	s_addc_u32 s17, s53, 0
	s_add_u32 s22, s52, 0x4a00
	s_addc_u32 s23, s53, 0
	s_add_u32 s36, s52, 0x4b00
	s_addc_u32 s37, s53, 0
	s_add_u32 s38, s52, 0x4c00
	s_addc_u32 s39, s53, 0
	s_add_u32 s40, s52, 0x4d00
	s_addc_u32 s41, s53, 0
	s_add_u32 s42, s52, 0x4e00
	s_addc_u32 s43, s53, 0
	s_add_u32 s44, s52, 0x4f00
	s_addc_u32 s45, s53, 0
	s_add_u32 s46, s52, 0x5000
	s_addc_u32 s47, s53, 0
	s_add_u32 s48, s52, 0x5100
	s_addc_u32 s49, s53, 0
	s_add_u32 s50, s52, 0x5200
	s_addc_u32 s51, s53, 0
	s_add_u32 s64, s52, 0x5300
	s_addc_u32 s65, s53, 0
	s_mov_b32 s26, 1
	v_mov_b32_e32 v17, 0
	s_branch .LBB0_785

; __device__ __forceinline__ unsigned xb_ld(unsigned* p)              { return __hip_atomic_load(p, __ATOMIC_RELAXED, __HIP_MEMORY_SCOPE_AGENT); }
; __device__ __forceinline__ void xcd_barrier_complete(unsigned* bar, unsigned x, unsigned& nloc, unsigned& nx) {
;     const unsigned G = gridDim.x * gridDim.y * gridDim.z;
;     unsigned sum, cnt, mine, sp = 0u;
;     for (;;) {
;         sum = 0u; cnt = 0u; mine = 0u;
; #pragma unroll
;         for (unsigned j = 0; j < 16; ++j) { const unsigned c = xb_ld(&bar[XB_XCNT(j)]); sum += c; cnt += (c > 0u) ? 1u : 0u; mine = (j == x) ? c : mine; }
; __device__ __forceinline__ void xcd_barrier(const XcdBarrier& b) {
;     asm volatile("s_waitcnt vmcnt(0)" ::: "memory");
;     __syncthreads();
;     if (threadIdx.x == 0) {
;         unsigned* bar = b.bar;
;         __builtin_amdgcn_s_waitcnt(0);
;         unsigned nloc = b.st[0], nx = b.st[1];
;         if (nloc == 0u) { xcd_barrier_complete(bar, b.x, nloc, nx); b.st[0] = nloc; b.st[1] = nx; }
.LBB0_855:
	s_cmp_gt_i32 s55, 12
	s_cselect_b64 s[0:1], -1, 0
	s_and_b64 s[4:5], s[8:9], s[0:1]
	s_andn2_b64 vcc, exec, s[4:5]
	s_cbranch_vccnz .LBB0_905
	s_waitcnt vmcnt(0)
	v_cmp_eq_u32_e32 vcc, 0, v0
	s_waitcnt lgkmcnt(0)
	s_barrier
	s_and_saveexec_b64 s[4:5], vcc
	s_cbranch_execz .LBB0_904
	v_mov_b32_e32 v1, s95
	s_waitcnt vmcnt(0) expcnt(0) lgkmcnt(0)
	buffer_wbl2 sc1
	ds_read_b32 v3, v1
	ds_read_b32 v1, v1 offset:4
	s_waitcnt lgkmcnt(1)
	v_cmp_ne_u32_e32 vcc, 0, v3
	s_cbranch_vccnz .LBB0_872
	v_readlane_b32 s8, v255, 9
	v_readlane_b32 s9, v255, 10
	s_load_dwordx2 s[12:13], s[8:9], 0x4
	s_add_u32 s8, s52, 0x4200
	s_addc_u32 s9, s53, 0
	s_add_u32 s10, s52, 0x4400
	s_addc_u32 s11, s53, 0
	s_waitcnt lgkmcnt(0)
	s_mul_i32 s3, s12, s60
	s_add_u32 s12, s52, 0x4500
	s_mul_i32 s3, s3, s13
	s_addc_u32 s13, s53, 0
	s_add_u32 s14, s52, 0x4600
	s_addc_u32 s15, s53, 0
	s_add_u32 s16, s52, 0x4700
	s_addc_u32 s17, s53, 0
	s_add_u32 s22, s52, 0x4800
	s_addc_u32 s23, s53, 0
	s_add_u32 s26, s52, 0x4900
	s_addc_u32 s27, s53, 0
	s_add_u32 s36, s52, 0x4a00
	s_addc_u32 s37, s53, 0
	s_add_u32 s38, s52, 0x4b00
	s_addc_u32 s39, s53, 0
	s_add_u32 s40, s52, 0x4c00
	s_addc_u32 s41, s53, 0
	s_add_u32 s42, s52, 0x4d00
	s_addc_u32 s43, s53, 0
	s_add_u32 s44, s52, 0x4e00
	s_addc_u32 s45, s53, 0
	s_add_u32 s46, s52, 0x4f00
	s_addc_u32 s47, s53, 0
	s_add_u32 s48, s52, 0x5000
	s_addc_u32 s49, s53, 0
	s_add_u32 s50, s52, 0x5100
	s_addc_u32 s51, s53, 0
	s_add_u32 s64, s52, 0x5200
	s_addc_u32 s65, s53, 0
	s_add_u32 s66, s52, 0x5300
	s_addc_u32 s67, s53, 0
	s_mov_b32 s28, 1
	v_mov_b32_e32 v17, 0
	s_branch .LBB0_860

; __device__ __forceinline__ unsigned xb_ld(unsigned* p)              { return __hip_atomic_load(p, __ATOMIC_RELAXED, __HIP_MEMORY_SCOPE_AGENT); }
; __device__ __forceinline__ void xcd_barrier_complete(unsigned* bar, unsigned x, unsigned& nloc, unsigned& nx) {
;     const unsigned G = gridDim.x * gridDim.y * gridDim.z;
;     unsigned sum, cnt, mine, sp = 0u;
;     for (;;) {
;         sum = 0u; cnt = 0u; mine = 0u;
; #pragma unroll
;         for (unsigned j = 0; j < 16; ++j) { const unsigned c = xb_ld(&bar[XB_XCNT(j)]); sum += c; cnt += (c > 0u) ? 1u : 0u; mine = (j == x) ? c : mine; }
; __device__ __forceinline__ void xcd_barrier(const XcdBarrier& b) {
;     asm volatile("s_waitcnt vmcnt(0)" ::: "memory");
;     __syncthreads();
;     if (threadIdx.x == 0) {
;         unsigned* bar = b.bar;
;         __builtin_amdgcn_s_waitcnt(0);
;         unsigned nloc = b.st[0], nx = b.st[1];
;         if (nloc == 0u) { xcd_barrier_complete(bar, b.x, nloc, nx); b.st[0] = nloc; b.st[1] = nx; }
.LBB0_996:
	s_and_b64 s[0:1], s[12:13], s[0:1]
	s_andn2_b64 vcc, exec, s[0:1]
	s_cbranch_vccnz .LBB0_1046
	s_waitcnt vmcnt(0)
	v_cmp_eq_u32_e32 vcc, 0, v0
	s_waitcnt lgkmcnt(0)
	s_barrier
	s_and_saveexec_b64 s[0:1], vcc
	s_cbranch_execz .LBB0_1045
	v_mov_b32_e32 v0, s95
	s_waitcnt vmcnt(0) expcnt(0) lgkmcnt(0)
	buffer_wbl2 sc1
	ds_read_b32 v2, v0
	ds_read_b32 v0, v0 offset:4
	s_waitcnt lgkmcnt(1)
	v_cmp_ne_u32_e32 vcc, 0, v2
	s_cbranch_vccnz .LBB0_1013
	v_readlane_b32 s2, v255, 9
	v_readlane_b32 s3, v255, 10
	s_load_dwordx2 s[6:7], s[2:3], 0x4
	s_add_u32 s2, s52, 0x4200
	s_addc_u32 s3, s53, 0
	s_add_u32 s4, s52, 0x4400
	s_addc_u32 s5, s53, 0
	s_waitcnt lgkmcnt(0)
	s_mul_i32 s28, s6, s60
	s_add_u32 s6, s52, 0x4500
	s_mul_i32 s28, s28, s7
	s_addc_u32 s7, s53, 0
	s_add_u32 s8, s52, 0x4600
	s_addc_u32 s9, s53, 0
	s_add_u32 s12, s52, 0x4700
	s_addc_u32 s13, s53, 0
	s_add_u32 s14, s52, 0x4800
	s_addc_u32 s15, s53, 0
	s_add_u32 s16, s52, 0x4900
	s_addc_u32 s17, s53, 0
	s_add_u32 s18, s52, 0x4a00
	s_addc_u32 s19, s53, 0
	s_add_u32 s20, s52, 0x4b00
	s_addc_u32 s21, s53, 0
	s_add_u32 s22, s52, 0x4c00
	s_addc_u32 s23, s53, 0
	s_add_u32 s24, s52, 0x4d00
	s_addc_u32 s25, s53, 0
	s_add_u32 s26, s52, 0x4e00
	s_addc_u32 s27, s53, 0
	s_add_u32 s36, s52, 0x4f00
	s_addc_u32 s37, s53, 0
	s_add_u32 s38, s52, 0x5000
	s_addc_u32 s39, s53, 0
	s_add_u32 s40, s52, 0x5100
	s_addc_u32 s41, s53, 0
	s_add_u32 s42, s52, 0x5200
	s_addc_u32 s43, s53, 0
	s_add_u32 s44, s52, 0x5300
	s_addc_u32 s45, s53, 0
	s_mov_b32 s29, 1
	v_mov_b32_e32 v16, 0
	s_branch .LBB0_1001
